# mod GEMV loop: next k-step's four strided weight loads issued one step ahead
# speedup vs baseline: 1.0055x; 1.0055x over previous
.LBB0_293:
	s_or_b64 exec, exec, s[4:5]
	s_mul_hi_i32 s1, s0, 0x2aaaaaab
	s_lshr_b32 s4, s1, 31
	s_ashr_i32 s1, s1, 3
	s_add_i32 s1, s1, s4
	s_mul_i32 s4, s1, 48
	s_sub_i32 s4, s0, s4
	s_lshl_b32 s14, s4, 7
	s_ashr_i32 s15, s14, 31
	s_mul_i32 s7, s1, 0x1800000
	s_lshl_b64 s[4:5], s[14:15], 2
	s_mul_hi_i32 s6, s1, 0x1800000
	s_add_u32 s4, s7, s4
	s_addc_u32 s5, s6, s5
	v_mov_b32_e32 v12, 0
	v_lshl_add_u64 v[14:15], v[8:9], 0, s[4:5]
	s_mov_b64 s[4:5], 0
	v_mov_b32_e32 v5, v89
	v_mov_b32_e32 v91, v88
	v_mov_b32_e32 v13, v12
	v_mov_b32_e32 v16, v12
	v_mov_b32_e32 v17, v12
	v_mov_b32_e32 v18, v12
	v_mov_b32_e32 v19, v12
	v_mov_b32_e32 v20, v12
	v_mov_b32_e32 v21, v12
	v_mov_b32_e32 v22, v12
	v_mov_b32_e32 v23, v12
	v_mov_b32_e32 v24, v12
	v_mov_b32_e32 v25, v12
	v_mov_b32_e32 v26, v12
	v_mov_b32_e32 v27, v12
	v_mov_b32_e32 v28, v12
	v_mov_b32_e32 v29, v12
	v_mov_b32_e32 v92, v12
	s_waitcnt lgkmcnt(0)
	s_barrier
	s_mov_b32 s6, 0xfffee000
	v_add_co_u32_e32 v108, vcc, s6, v14
	s_nop 1
	v_addc_co_u32_e32 v109, vcc, -1, v15, vcc
	global_load_dword v104, v[108:109], off
	s_mov_b32 s6, 0xffff4000
	v_add_co_u32_e32 v108, vcc, s6, v14
	s_nop 1
	v_addc_co_u32_e32 v109, vcc, -1, v15, vcc
	global_load_dword v105, v[108:109], off
	s_movk_i32 s6, 0xa000
	v_add_co_u32_e32 v108, vcc, s6, v14
	s_nop 1
	v_addc_co_u32_e32 v109, vcc, -1, v15, vcc
	global_load_dword v106, v[108:109], off
	global_load_dword v107, v[14:15], off
.LBB0_294:
	s_waitcnt vmcnt(0)
	v_mov_b32_e32 v30, v104
	v_mov_b32_e32 v32, v105
	v_mov_b32_e32 v34, v106
	v_mov_b32_e32 v36, v107
	s_nop 0
	s_nop 0
	v_add_u32_e32 v91, 4, v91
	s_nop 0
	s_nop 0
	ds_read_b128 v[94:97], v5
	ds_read_b128 v[98:101], v5 offset:4096
	s_mov_b64 s[6:7], 0x18000
	v_cmp_ge_i32_e32 vcc, v91, v3
	v_lshl_add_u64 v[14:15], v[14:15], 0, s[6:7]
	s_waitcnt lgkmcnt(1)
	v_mov_b32_e32 v102, v94
	s_waitcnt lgkmcnt(0)
	v_mov_b32_e32 v103, v98
	v_mov_b32_e32 v98, v95
	s_or_b64 s[4:5], vcc, s[4:5]
	s_and_b64 vcc, exec, s[4:5]
	s_cbranch_vccnz .Lmod_nopf
	s_mov_b32 s6, 0xfffee000
	v_add_co_u32_e32 v108, vcc, s6, v14
	s_nop 1
	v_addc_co_u32_e32 v109, vcc, -1, v15, vcc
	global_load_dword v104, v[108:109], off
	s_mov_b32 s6, 0xffff4000
	v_add_co_u32_e32 v108, vcc, s6, v14
	s_nop 1
	v_addc_co_u32_e32 v109, vcc, -1, v15, vcc
	global_load_dword v105, v[108:109], off
	s_movk_i32 s6, 0xa000
	v_add_co_u32_e32 v108, vcc, s6, v14
	s_nop 1
	v_addc_co_u32_e32 v109, vcc, -1, v15, vcc
	global_load_dword v106, v[108:109], off
	global_load_dword v107, v[14:15], off
.Lmod_nopf:
	v_pk_mul_f32 v[94:95], v[32:33], v[98:99] op_sel_hi:[0,1]
	v_pk_fma_f32 v[94:95], v[30:31], v[102:103], v[94:95] op_sel_hi:[0,1,1]
	v_mov_b32_e32 v98, v96
	v_mov_b32_e32 v99, v100
	v_mov_b32_e32 v100, v97
	v_pk_fma_f32 v[94:95], v[34:35], v[98:99], v[94:95] op_sel_hi:[0,1,1]
	v_pk_fma_f32 v[94:95], v[36:37], v[100:101], v[94:95] op_sel_hi:[0,1,1]
	v_pk_add_f32 v[12:13], v[12:13], v[94:95]
	ds_read_b128 v[94:97], v5 offset:8192
	ds_read_b128 v[98:101], v5 offset:12288
	s_waitcnt lgkmcnt(1)
	v_mov_b32_e32 v102, v94
	s_waitcnt lgkmcnt(0)
	v_mov_b32_e32 v103, v98
	v_mov_b32_e32 v98, v95
	v_pk_mul_f32 v[94:95], v[32:33], v[98:99] op_sel_hi:[0,1]
	v_pk_fma_f32 v[94:95], v[30:31], v[102:103], v[94:95] op_sel_hi:[0,1,1]
	v_mov_b32_e32 v98, v96
	v_mov_b32_e32 v99, v100
	v_pk_fma_f32 v[94:95], v[34:35], v[98:99], v[94:95] op_sel_hi:[0,1,1]
	v_mov_b32_e32 v100, v97
	v_pk_fma_f32 v[94:95], v[36:37], v[100:101], v[94:95] op_sel_hi:[0,1,1]
	v_pk_add_f32 v[16:17], v[16:17], v[94:95]
	ds_read_b128 v[94:97], v5 offset:16384
	ds_read_b128 v[98:101], v5 offset:20480
	s_waitcnt lgkmcnt(1)
	v_mov_b32_e32 v102, v94
	s_waitcnt lgkmcnt(0)
	v_mov_b32_e32 v103, v98
	v_mov_b32_e32 v98, v95
	v_pk_mul_f32 v[94:95], v[32:33], v[98:99] op_sel_hi:[0,1]
	v_pk_fma_f32 v[94:95], v[30:31], v[102:103], v[94:95] op_sel_hi:[0,1,1]
	v_mov_b32_e32 v98, v96
	v_mov_b32_e32 v99, v100
	v_pk_fma_f32 v[94:95], v[34:35], v[98:99], v[94:95] op_sel_hi:[0,1,1]
	v_mov_b32_e32 v100, v97
	v_pk_fma_f32 v[94:95], v[36:37], v[100:101], v[94:95] op_sel_hi:[0,1,1]
	v_pk_add_f32 v[18:19], v[18:19], v[94:95]
	ds_read_b128 v[94:97], v5 offset:24576
	ds_read_b128 v[98:101], v5 offset:28672
	s_waitcnt lgkmcnt(1)
	v_mov_b32_e32 v102, v94
	s_waitcnt lgkmcnt(0)
	v_mov_b32_e32 v103, v98
	v_mov_b32_e32 v98, v95
	v_pk_mul_f32 v[94:95], v[32:33], v[98:99] op_sel_hi:[0,1]
	v_pk_fma_f32 v[94:95], v[30:31], v[102:103], v[94:95] op_sel_hi:[0,1,1]
	v_mov_b32_e32 v98, v96
	v_mov_b32_e32 v99, v100
	v_pk_fma_f32 v[94:95], v[34:35], v[98:99], v[94:95] op_sel_hi:[0,1,1]
	v_mov_b32_e32 v100, v97
	v_pk_fma_f32 v[94:95], v[36:37], v[100:101], v[94:95] op_sel_hi:[0,1,1]
	v_pk_add_f32 v[20:21], v[20:21], v[94:95]
	ds_read_b128 v[94:97], v5 offset:32768
	ds_read_b128 v[98:101], v5 offset:36864
	s_waitcnt lgkmcnt(1)
	v_mov_b32_e32 v102, v94
	s_waitcnt lgkmcnt(0)
	v_mov_b32_e32 v103, v98
	v_mov_b32_e32 v98, v95
	v_pk_mul_f32 v[94:95], v[32:33], v[98:99] op_sel_hi:[0,1]
	v_pk_fma_f32 v[94:95], v[30:31], v[102:103], v[94:95] op_sel_hi:[0,1,1]
	v_mov_b32_e32 v98, v96
	v_mov_b32_e32 v99, v100
	v_pk_fma_f32 v[94:95], v[34:35], v[98:99], v[94:95] op_sel_hi:[0,1,1]
	v_mov_b32_e32 v100, v97
	v_pk_fma_f32 v[94:95], v[36:37], v[100:101], v[94:95] op_sel_hi:[0,1,1]
	v_pk_add_f32 v[22:23], v[22:23], v[94:95]
	ds_read_b128 v[94:97], v5 offset:40960
	ds_read_b128 v[98:101], v5 offset:45056
	s_waitcnt lgkmcnt(1)
	v_mov_b32_e32 v102, v94
	s_waitcnt lgkmcnt(0)
	v_mov_b32_e32 v103, v98
	v_mov_b32_e32 v98, v95
	v_pk_mul_f32 v[94:95], v[32:33], v[98:99] op_sel_hi:[0,1]
	v_pk_fma_f32 v[94:95], v[30:31], v[102:103], v[94:95] op_sel_hi:[0,1,1]
	v_mov_b32_e32 v98, v96
	v_mov_b32_e32 v99, v100
	v_pk_fma_f32 v[94:95], v[34:35], v[98:99], v[94:95] op_sel_hi:[0,1,1]
	v_mov_b32_e32 v100, v97
	v_pk_fma_f32 v[94:95], v[36:37], v[100:101], v[94:95] op_sel_hi:[0,1,1]
	v_pk_add_f32 v[24:25], v[24:25], v[94:95]
	ds_read_b128 v[94:97], v5 offset:49152
	ds_read_b128 v[98:101], v5 offset:53248
	s_waitcnt lgkmcnt(1)
	v_mov_b32_e32 v102, v94
	s_waitcnt lgkmcnt(0)
	v_mov_b32_e32 v103, v98
	v_mov_b32_e32 v98, v95
	v_pk_mul_f32 v[94:95], v[32:33], v[98:99] op_sel_hi:[0,1]
	v_pk_fma_f32 v[94:95], v[30:31], v[102:103], v[94:95] op_sel_hi:[0,1,1]
	v_mov_b32_e32 v98, v96
	v_mov_b32_e32 v99, v100
	v_pk_fma_f32 v[94:95], v[34:35], v[98:99], v[94:95] op_sel_hi:[0,1,1]
	v_mov_b32_e32 v100, v97
	v_pk_fma_f32 v[94:95], v[36:37], v[100:101], v[94:95] op_sel_hi:[0,1,1]
	v_pk_add_f32 v[26:27], v[26:27], v[94:95]
	ds_read_b128 v[94:97], v5 offset:57344
	ds_read_b128 v[98:101], v5 offset:61440
	s_waitcnt lgkmcnt(1)
	v_mov_b32_e32 v102, v94
	s_waitcnt lgkmcnt(0)
	v_mov_b32_e32 v103, v98
	v_mov_b32_e32 v98, v95
	v_pk_mul_f32 v[94:95], v[32:33], v[98:99] op_sel_hi:[0,1]
	v_pk_fma_f32 v[94:95], v[30:31], v[102:103], v[94:95] op_sel_hi:[0,1,1]
	v_mov_b32_e32 v98, v96
	v_mov_b32_e32 v99, v100
	v_pk_fma_f32 v[94:95], v[34:35], v[98:99], v[94:95] op_sel_hi:[0,1,1]
	v_mov_b32_e32 v100, v97
	v_pk_fma_f32 v[94:95], v[36:37], v[100:101], v[94:95] op_sel_hi:[0,1,1]
	v_add_u32_e32 v31, 0x10000, v5
	v_pk_add_f32 v[28:29], v[28:29], v[94:95]
	ds_read_b128 v[94:97], v31
	v_mov_b32_e32 v31, v32
	v_mov_b32_e32 v35, v36
	v_add_u32_e32 v5, 16, v5
	s_waitcnt lgkmcnt(0)
	v_pk_mul_f32 v[30:31], v[30:31], v[94:95]
	v_pk_mul_f32 v[34:35], v[34:35], v[96:97]
	v_add_f32_e32 v30, v30, v31
	v_add_f32_e32 v30, v30, v34
	v_add_f32_e32 v30, v30, v35
	v_add_f32_e32 v92, v92, v30
	s_andn2_b64 exec, exec, s[4:5]
	s_cbranch_execnz .LBB0_294
	s_or_b64 exec, exec, s[4:5]
	ds_write2st64_b32 v90, v12, v13 offset1:2
	ds_write2st64_b32 v90, v16, v17 offset0:4 offset1:6
	ds_write2st64_b32 v90, v18, v19 offset0:8 offset1:10
	ds_write2st64_b32 v90, v20, v21 offset0:12 offset1:14
	ds_write2st64_b32 v90, v22, v23 offset0:16 offset1:18
	ds_write2st64_b32 v90, v24, v25 offset0:20 offset1:22
	ds_write2st64_b32 v90, v26, v27 offset0:24 offset1:26
	ds_write2st64_b32 v90, v28, v29 offset0:28 offset1:30
	ds_write_b32 v90, v92 offset:8192
	s_waitcnt lgkmcnt(0)
	s_barrier
	s_and_saveexec_b64 s[4:5], s[10:11]
	s_cbranch_execz .LBB0_289
	s_mul_i32 s6, s1, 0x1800
	s_add_i32 s6, s6, s14
	v_or_b32_e32 v12, s6, v4
	v_readlane_b32 s6, v254, 41
	v_readlane_b32 s7, v254, 42
	s_load_dwordx2 s[6:7], s[6:7], 0x28
	v_ashrrev_i32_e32 v13, 31, v12
	s_waitcnt lgkmcnt(0)
	v_lshl_add_u64 v[12:13], v[12:13], 2, s[6:7]
	global_load_dword v5, v[12:13], off
	ds_read2st64_b32 v[14:15], v1 offset1:2
	ds_read_b32 v16, v33
	v_lshl_add_u64 v[12:13], s[14:15], 2, v[6:7]
	v_mad_i64_i32 v[12:13], s[6:7], s1, v237, v[12:13]
	s_movk_i32 s1, 0x6000
	s_waitcnt lgkmcnt(0)
	v_add_f32_e32 v14, v14, v16
	ds_read_b32 v16, v37
	s_waitcnt lgkmcnt(0)
	v_add_f32_e32 v14, v14, v16
	ds_read_b32 v16, v38
	s_waitcnt lgkmcnt(0)
	v_add_f32_e32 v14, v14, v16
	s_waitcnt vmcnt(0)
	v_add_f32_e32 v14, v5, v14
	global_store_dword v[12:13], v14, off
	ds_read_b32 v14, v39
	s_waitcnt lgkmcnt(0)
	v_add_f32_e32 v14, v15, v14
	ds_read_b32 v15, v40
	s_waitcnt lgkmcnt(0)
	v_add_f32_e32 v14, v14, v15
	ds_read_b32 v15, v41
	s_waitcnt lgkmcnt(0)
	v_add_f32_e32 v14, v14, v15
	v_add_f32_e32 v16, v5, v14
	v_add_co_u32_e32 v14, vcc, s1, v12
	s_mov_b32 s1, 0xc000
	s_nop 0
	v_addc_co_u32_e32 v15, vcc, 0, v13, vcc
	global_store_dword v[14:15], v16, off
	ds_read2st64_b32 v[14:15], v1 offset0:4 offset1:6
	ds_read_b32 v16, v42
	s_waitcnt lgkmcnt(0)
	v_add_f32_e32 v14, v14, v16
	ds_read_b32 v16, v43
	s_waitcnt lgkmcnt(0)
	v_add_f32_e32 v14, v14, v16
	ds_read_b32 v16, v44
	s_waitcnt lgkmcnt(0)
	v_add_f32_e32 v14, v14, v16
	v_add_co_u32_e32 v16, vcc, s1, v12
	v_add_f32_e32 v14, v5, v14
	s_nop 0
	v_addc_co_u32_e32 v17, vcc, 0, v13, vcc
	global_store_dword v[16:17], v14, off
	ds_read_b32 v14, v45
	s_mov_b32 s1, 0x12000
	s_waitcnt lgkmcnt(0)
	v_add_f32_e32 v14, v15, v14
	ds_read_b32 v15, v46
	s_waitcnt lgkmcnt(0)
	v_add_f32_e32 v14, v14, v15
	ds_read_b32 v15, v47
	s_waitcnt lgkmcnt(0)
	v_add_f32_e32 v14, v14, v15
	v_add_f32_e32 v16, v5, v14
	v_add_co_u32_e32 v14, vcc, s1, v12
	s_mov_b32 s1, 0x18000
	s_nop 0
	v_addc_co_u32_e32 v15, vcc, 0, v13, vcc
	global_store_dword v[14:15], v16, off
	ds_read2st64_b32 v[14:15], v1 offset0:8 offset1:10
	ds_read_b32 v16, v48
	s_waitcnt lgkmcnt(0)
	v_add_f32_e32 v14, v14, v16
	ds_read_b32 v16, v49
	s_waitcnt lgkmcnt(0)
	v_add_f32_e32 v14, v14, v16
	ds_read_b32 v16, v50
	s_waitcnt lgkmcnt(0)
	v_add_f32_e32 v14, v14, v16
	v_add_co_u32_e32 v16, vcc, s1, v12
	v_add_f32_e32 v14, v5, v14
	s_nop 0
	v_addc_co_u32_e32 v17, vcc, 0, v13, vcc
	global_store_dword v[16:17], v14, off
	ds_read_b32 v14, v51
	s_mov_b32 s1, 0x1e000
	s_waitcnt lgkmcnt(0)
	v_add_f32_e32 v14, v15, v14
	ds_read_b32 v15, v52
	s_waitcnt lgkmcnt(0)
	v_add_f32_e32 v14, v14, v15
	ds_read_b32 v15, v53
	s_waitcnt lgkmcnt(0)
	v_add_f32_e32 v14, v14, v15
	v_add_f32_e32 v16, v5, v14
	v_add_co_u32_e32 v14, vcc, s1, v12
	s_mov_b32 s1, 0x24000
	s_nop 0
	v_addc_co_u32_e32 v15, vcc, 0, v13, vcc
	global_store_dword v[14:15], v16, off
	ds_read2st64_b32 v[14:15], v1 offset0:12 offset1:14
	ds_read_b32 v16, v54
	s_waitcnt lgkmcnt(0)
	v_add_f32_e32 v14, v14, v16
	ds_read_b32 v16, v55
	s_waitcnt lgkmcnt(0)
	v_add_f32_e32 v14, v14, v16
	ds_read_b32 v16, v56
	s_waitcnt lgkmcnt(0)
	v_add_f32_e32 v14, v14, v16
	v_add_co_u32_e32 v16, vcc, s1, v12
	v_add_f32_e32 v14, v5, v14
	s_nop 0
	v_addc_co_u32_e32 v17, vcc, 0, v13, vcc
	global_store_dword v[16:17], v14, off
	ds_read_b32 v14, v57
	s_mov_b32 s1, 0x2a000
	s_waitcnt lgkmcnt(0)
	v_add_f32_e32 v14, v15, v14
	ds_read_b32 v15, v58
	s_waitcnt lgkmcnt(0)
	v_add_f32_e32 v14, v14, v15
	ds_read_b32 v15, v59
	s_waitcnt lgkmcnt(0)
	v_add_f32_e32 v14, v14, v15
	v_add_f32_e32 v16, v5, v14
	v_add_co_u32_e32 v14, vcc, s1, v12
	s_mov_b32 s1, 0x30000
	s_nop 0
	v_addc_co_u32_e32 v15, vcc, 0, v13, vcc
	global_store_dword v[14:15], v16, off
	ds_read2st64_b32 v[14:15], v1 offset0:16 offset1:18
	ds_read_b32 v16, v60
	s_waitcnt lgkmcnt(0)
	v_add_f32_e32 v14, v14, v16
	ds_read_b32 v16, v61
	s_waitcnt lgkmcnt(0)
	v_add_f32_e32 v14, v14, v16
	ds_read_b32 v16, v62
	s_waitcnt lgkmcnt(0)
	v_add_f32_e32 v14, v14, v16
	v_add_co_u32_e32 v16, vcc, s1, v12
	v_add_f32_e32 v14, v5, v14
	s_nop 0
	v_addc_co_u32_e32 v17, vcc, 0, v13, vcc
	global_store_dword v[16:17], v14, off
	ds_read_b32 v14, v63
	s_mov_b32 s1, 0x36000
	s_waitcnt lgkmcnt(0)
	v_add_f32_e32 v14, v15, v14
	ds_read_b32 v15, v64
	s_waitcnt lgkmcnt(0)
	v_add_f32_e32 v14, v14, v15
	ds_read_b32 v15, v65
	s_waitcnt lgkmcnt(0)
	v_add_f32_e32 v14, v14, v15
	v_add_f32_e32 v16, v5, v14
	v_add_co_u32_e32 v14, vcc, s1, v12
	s_mov_b32 s1, 0x3c000
	s_nop 0
	v_addc_co_u32_e32 v15, vcc, 0, v13, vcc
	global_store_dword v[14:15], v16, off
	ds_read2st64_b32 v[14:15], v1 offset0:20 offset1:22
	ds_read_b32 v16, v66
	s_waitcnt lgkmcnt(0)
	v_add_f32_e32 v14, v14, v16
	ds_read_b32 v16, v67
	s_waitcnt lgkmcnt(0)
	v_add_f32_e32 v14, v14, v16
	ds_read_b32 v16, v68
	s_waitcnt lgkmcnt(0)
	v_add_f32_e32 v14, v14, v16
	v_add_co_u32_e32 v16, vcc, s1, v12
	v_add_f32_e32 v14, v5, v14
	s_nop 0
	v_addc_co_u32_e32 v17, vcc, 0, v13, vcc
	global_store_dword v[16:17], v14, off
	ds_read_b32 v14, v69
	s_mov_b32 s1, 0x42000
	s_waitcnt lgkmcnt(0)
	v_add_f32_e32 v14, v15, v14
	ds_read_b32 v15, v70
	s_waitcnt lgkmcnt(0)
	v_add_f32_e32 v14, v14, v15
	ds_read_b32 v15, v71
	s_waitcnt lgkmcnt(0)
	v_add_f32_e32 v14, v14, v15
	v_add_f32_e32 v16, v5, v14
	v_add_co_u32_e32 v14, vcc, s1, v12
	s_mov_b32 s1, 0x48000
	s_nop 0
	v_addc_co_u32_e32 v15, vcc, 0, v13, vcc
	global_store_dword v[14:15], v16, off
	ds_read2st64_b32 v[14:15], v1 offset0:24 offset1:26
	ds_read_b32 v16, v72
	s_waitcnt lgkmcnt(0)
	v_add_f32_e32 v14, v14, v16
	ds_read_b32 v16, v73
	s_waitcnt lgkmcnt(0)
	v_add_f32_e32 v14, v14, v16
	ds_read_b32 v16, v74
	s_waitcnt lgkmcnt(0)
	v_add_f32_e32 v14, v14, v16
	v_add_co_u32_e32 v16, vcc, s1, v12
	v_add_f32_e32 v14, v5, v14
	s_nop 0
	v_addc_co_u32_e32 v17, vcc, 0, v13, vcc
	global_store_dword v[16:17], v14, off
	ds_read_b32 v14, v75
	s_mov_b32 s1, 0x4e000
	s_waitcnt lgkmcnt(0)
	v_add_f32_e32 v14, v15, v14
	ds_read_b32 v15, v76
	s_waitcnt lgkmcnt(0)
	v_add_f32_e32 v14, v14, v15
	ds_read_b32 v15, v77
	s_waitcnt lgkmcnt(0)
	v_add_f32_e32 v14, v14, v15
	v_add_f32_e32 v16, v5, v14
	v_add_co_u32_e32 v14, vcc, s1, v12
	s_mov_b32 s1, 0x54000
	s_nop 0
	v_addc_co_u32_e32 v15, vcc, 0, v13, vcc
	global_store_dword v[14:15], v16, off
	ds_read2st64_b32 v[14:15], v1 offset0:28 offset1:30
	ds_read_b32 v16, v78
	s_waitcnt lgkmcnt(0)
	v_add_f32_e32 v14, v14, v16
	ds_read_b32 v16, v79
	s_waitcnt lgkmcnt(0)
	v_add_f32_e32 v14, v14, v16
	ds_read_b32 v16, v80
	s_waitcnt lgkmcnt(0)
	v_add_f32_e32 v14, v14, v16
	v_add_co_u32_e32 v16, vcc, s1, v12
	v_add_f32_e32 v14, v5, v14
	s_nop 0
	v_addc_co_u32_e32 v17, vcc, 0, v13, vcc
	global_store_dword v[16:17], v14, off
	ds_read_b32 v14, v81
	s_waitcnt lgkmcnt(0)
	v_add_f32_e32 v14, v15, v14
	ds_read_b32 v15, v82
	s_waitcnt lgkmcnt(0)
	v_add_f32_e32 v14, v14, v15
	ds_read_b32 v15, v83
	s_waitcnt lgkmcnt(0)
	v_add_f32_e32 v14, v14, v15
	v_add_f32_e32 v16, v5, v14
	v_add_co_u32_e32 v14, vcc, 0x5a000, v12
	s_nop 1
	v_addc_co_u32_e32 v15, vcc, 0, v13, vcc
	global_store_dword v[14:15], v16, off
	ds_read_b32 v14, v1 offset:8192
	ds_read_b32 v15, v84
	v_add_co_u32_e32 v12, vcc, 0x60000, v12
	s_waitcnt lgkmcnt(0)
	v_add_f32_e32 v14, v14, v15
	ds_read_b32 v15, v85
	v_addc_co_u32_e32 v13, vcc, 0, v13, vcc
	s_waitcnt lgkmcnt(0)
	v_add_f32_e32 v14, v14, v15
	ds_read_b32 v15, v86
	s_waitcnt lgkmcnt(0)
	v_add_f32_e32 v14, v14, v15
	v_add_f32_e32 v5, v5, v14
	global_store_dword v[12:13], v5, off
	s_branch .LBB0_289
